# stack of load de-serialisations: gla_prep q/k prefetch one group ahead, final_norm 4-element batches, pool_prep 8-row batches (on top of ssd_conv batches and phase-0 scale hoist)
# speedup vs baseline: 1.0074x; 1.0021x over previous
; DI float rs_of(float ss, float inv_n) { return __builtin_amdgcn_rsqf(ss * inv_n + EPS); }
; DI float sum16(const float* p) { const f32x4 a = *(const f32x4*)p, b = *(const f32x4*)(p + 4), c = *(const f32x4*)(p + 8), d = *(const f32x4*)(p + 12); const f32x4 s = (a + b) + (c + d); return (s[0] + s[1]) + (s[2] + s[3]); }
; DI void final_norm(const Params& P) {
;     ...
;     for (int i = gt; i < T * 256; i += NT) { const int row = i >> 8, c4 = (i & 255) * 4; const float rs = rs_of(sum16(SS + (size_t)row * 16), 1.f / 1024.f);
;         const f32x4 v = *(const f32x4*)(X + (size_t)row * DM + c4) * *(const f32x4*)(g + c4) * rs; *(f32x4*)(P.out + OUT_Y + (size_t)row * DM + c4) = v; }
.LBB0_91:
	v_and_b32_e32 v20, 0x3fc, v0
	v_lshlrev_b32_e32 v24, 2, v20
	v_add_u32_e32 v0, s16, v0
	s_mov_b32 s17, 0x41ffff
	v_ashrrev_i32_e32 v18, 8, v1
	v_add_u32_e32 v26, s3, v1
	v_ashrrev_i32_e32 v20, 8, v26
	v_add_u32_e32 v26, s3, v26
	v_ashrrev_i32_e32 v22, 8, v26
	v_add_u32_e32 v26, s3, v26
	v_ashrrev_i32_e32 v28, 8, v26
	v_add_u32_e32 v1, s3, v26
	s_waitcnt lgkmcnt(0)
	global_load_dwordx4 v[148:151], v24, s[10:11]
	v_ashrrev_i32_e32 v19, 31, v18
	v_lshlrev_b64 v[30:31], 6, v[18:19]
	v_lshl_add_u64 v[30:31], s[8:9], 0, v[30:31]
	global_load_dwordx4 v[68:71], v[30:31], off offset:32
	global_load_dwordx4 v[72:75], v[30:31], off offset:48
	global_load_dwordx4 v[76:79], v[30:31], off
	global_load_dwordx4 v[80:83], v[30:31], off offset:16
	v_lshlrev_b64 v[152:153], 12, v[18:19]
	v_lshl_add_u64 v[30:31], s[6:7], 0, v[152:153]
	v_lshl_add_u64 v[30:31], v[30:31], 0, v[24:25]
	global_load_dwordx4 v[132:135], v[30:31], off
	v_ashrrev_i32_e32 v21, 31, v20
	v_lshlrev_b64 v[30:31], 6, v[20:21]
	v_lshl_add_u64 v[30:31], s[8:9], 0, v[30:31]
	global_load_dwordx4 v[84:87], v[30:31], off offset:32
	global_load_dwordx4 v[88:91], v[30:31], off offset:48
	global_load_dwordx4 v[92:95], v[30:31], off
	global_load_dwordx4 v[96:99], v[30:31], off offset:16
	v_lshlrev_b64 v[154:155], 12, v[20:21]
	v_lshl_add_u64 v[30:31], s[6:7], 0, v[154:155]
	v_lshl_add_u64 v[30:31], v[30:31], 0, v[24:25]
	global_load_dwordx4 v[136:139], v[30:31], off
	v_ashrrev_i32_e32 v23, 31, v22
	v_lshlrev_b64 v[30:31], 6, v[22:23]
	v_lshl_add_u64 v[30:31], s[8:9], 0, v[30:31]
	global_load_dwordx4 v[100:103], v[30:31], off offset:32
	global_load_dwordx4 v[104:107], v[30:31], off offset:48
	global_load_dwordx4 v[108:111], v[30:31], off
	global_load_dwordx4 v[112:115], v[30:31], off offset:16
	v_lshlrev_b64 v[156:157], 12, v[22:23]
	v_lshl_add_u64 v[30:31], s[6:7], 0, v[156:157]
	v_lshl_add_u64 v[30:31], v[30:31], 0, v[24:25]
	global_load_dwordx4 v[140:143], v[30:31], off
	v_ashrrev_i32_e32 v29, 31, v28
	v_lshlrev_b64 v[30:31], 6, v[28:29]
	v_lshl_add_u64 v[30:31], s[8:9], 0, v[30:31]
	global_load_dwordx4 v[116:119], v[30:31], off offset:32
	global_load_dwordx4 v[120:123], v[30:31], off offset:48
	global_load_dwordx4 v[124:127], v[30:31], off
	global_load_dwordx4 v[128:131], v[30:31], off offset:16
	v_lshlrev_b64 v[158:159], 12, v[28:29]
	v_lshl_add_u64 v[30:31], s[6:7], 0, v[158:159]
	v_lshl_add_u64 v[30:31], v[30:31], 0, v[24:25]
	global_load_dwordx4 v[144:147], v[30:31], off
	v_cmp_lt_i32_e32 vcc, s17, v1
	s_or_b64 s[14:15], vcc, s[14:15]
	s_waitcnt vmcnt(0)
	v_pk_add_f32 v[70:71], v[70:71], v[74:75]
	v_pk_add_f32 v[68:69], v[68:69], v[72:73]
	v_pk_add_f32 v[78:79], v[78:79], v[82:83]
	v_pk_add_f32 v[76:77], v[76:77], v[80:81]
	v_pk_add_f32 v[70:71], v[78:79], v[70:71]
	v_pk_add_f32 v[68:69], v[76:77], v[68:69]
	v_pk_mov_b32 v[168:169], v[68:69], v[70:71] op_sel:[1,0]
	v_mov_b32_e32 v69, v71
	v_pk_add_f32 v[68:69], v[168:169], v[68:69]
	s_nop 0
	v_add_f32_e32 v68, v68, v69
	v_fmamk_f32 v68, v68, 0x3a800000, v185
	v_rsq_f32_e32 v170, v68
	v_pk_mul_f32 v[134:135], v[134:135], v[150:151]
	v_pk_mul_f32 v[132:133], v[132:133], v[148:149]
	v_lshl_add_u64 v[30:31], s[12:13], 0, v[152:153]
	v_pk_mul_f32 v[134:135], v[134:135], v[170:171] op_sel_hi:[1,0]
	v_pk_mul_f32 v[132:133], v[132:133], v[170:171] op_sel_hi:[1,0]
	v_lshl_add_u64 v[30:31], v[30:31], 0, v[24:25]
	global_store_dwordx4 v[30:31], v[132:135], off
	v_pk_add_f32 v[86:87], v[86:87], v[90:91]
	v_pk_add_f32 v[84:85], v[84:85], v[88:89]
	v_pk_add_f32 v[94:95], v[94:95], v[98:99]
	v_pk_add_f32 v[92:93], v[92:93], v[96:97]
	v_pk_add_f32 v[86:87], v[94:95], v[86:87]
	v_pk_add_f32 v[84:85], v[92:93], v[84:85]
	v_pk_mov_b32 v[168:169], v[84:85], v[86:87] op_sel:[1,0]
	v_mov_b32_e32 v85, v87
	v_pk_add_f32 v[84:85], v[168:169], v[84:85]
	s_nop 0
	v_add_f32_e32 v84, v84, v85
	v_fmamk_f32 v84, v84, 0x3a800000, v185
	v_rsq_f32_e32 v172, v84
	v_pk_mul_f32 v[138:139], v[138:139], v[150:151]
	v_pk_mul_f32 v[136:137], v[136:137], v[148:149]
	v_lshl_add_u64 v[30:31], s[12:13], 0, v[154:155]
	v_pk_mul_f32 v[138:139], v[138:139], v[172:173] op_sel_hi:[1,0]
	v_pk_mul_f32 v[136:137], v[136:137], v[172:173] op_sel_hi:[1,0]
	v_lshl_add_u64 v[30:31], v[30:31], 0, v[24:25]
	global_store_dwordx4 v[30:31], v[136:139], off
	v_pk_add_f32 v[102:103], v[102:103], v[106:107]
	v_pk_add_f32 v[100:101], v[100:101], v[104:105]
	v_pk_add_f32 v[110:111], v[110:111], v[114:115]
	v_pk_add_f32 v[108:109], v[108:109], v[112:113]
	v_pk_add_f32 v[102:103], v[110:111], v[102:103]
	v_pk_add_f32 v[100:101], v[108:109], v[100:101]
	v_pk_mov_b32 v[168:169], v[100:101], v[102:103] op_sel:[1,0]
	v_mov_b32_e32 v101, v103
	v_pk_add_f32 v[100:101], v[168:169], v[100:101]
	s_nop 0
	v_add_f32_e32 v100, v100, v101
	v_fmamk_f32 v100, v100, 0x3a800000, v185
	v_rsq_f32_e32 v174, v100
	v_pk_mul_f32 v[142:143], v[142:143], v[150:151]
	v_pk_mul_f32 v[140:141], v[140:141], v[148:149]
	v_lshl_add_u64 v[30:31], s[12:13], 0, v[156:157]
	v_pk_mul_f32 v[142:143], v[142:143], v[174:175] op_sel_hi:[1,0]
	v_pk_mul_f32 v[140:141], v[140:141], v[174:175] op_sel_hi:[1,0]
	v_lshl_add_u64 v[30:31], v[30:31], 0, v[24:25]
	global_store_dwordx4 v[30:31], v[140:143], off
	v_pk_add_f32 v[118:119], v[118:119], v[122:123]
	v_pk_add_f32 v[116:117], v[116:117], v[120:121]
	v_pk_add_f32 v[126:127], v[126:127], v[130:131]
	v_pk_add_f32 v[124:125], v[124:125], v[128:129]
	v_pk_add_f32 v[118:119], v[126:127], v[118:119]
	v_pk_add_f32 v[116:117], v[124:125], v[116:117]
	v_pk_mov_b32 v[168:169], v[116:117], v[118:119] op_sel:[1,0]
	v_mov_b32_e32 v117, v119
	v_pk_add_f32 v[116:117], v[168:169], v[116:117]
	s_nop 0
	v_add_f32_e32 v116, v116, v117
	v_fmamk_f32 v116, v116, 0x3a800000, v185
	v_rsq_f32_e32 v176, v116
	v_pk_mul_f32 v[146:147], v[146:147], v[150:151]
	v_pk_mul_f32 v[144:145], v[144:145], v[148:149]
	v_lshl_add_u64 v[30:31], s[12:13], 0, v[158:159]
	v_pk_mul_f32 v[146:147], v[146:147], v[176:177] op_sel_hi:[1,0]
	v_pk_mul_f32 v[144:145], v[144:145], v[176:177] op_sel_hi:[1,0]
	v_lshl_add_u64 v[30:31], v[30:31], 0, v[24:25]
	global_store_dwordx4 v[30:31], v[144:147], off
	s_andn2_b64 exec, exec, s[14:15]
	s_cbranch_execnz .LBB0_91

; #define LAS __attribute__((address_space(3)))
; DI float bf2f(bf16_t b) { return __uint_as_float(((unsigned)b) << 16); }
; DI bf16_t f2bf(float f) { return (bf16_t)(pk2(f, 0.f) & 0xffffu); }
; DI void gla_prep(const Params& P, LAS unsigned char* lds) {
;     ...
;         for (int t = 0; t < nt; ++t) { const int row = row0 + t; float z = ba;
; #pragma unroll
;             for (int r4 = 0; r4 < 4; ++r4) { const f32x4 tv = *(const LAS f32x4*)(t16s + t * 16 + 4 * r4); z += tv[0] * w2[4 * r4] + tv[1] * w2[4 * r4 + 1] + tv[2] * w2[4 * r4 + 2] + tv[3] * w2[4 * r4 + 3]; }
;             const float la = (fminf(z, 0.f) - __logf(1.0f + __expf(-fabsf(z)))) * (1.f / 16.f);
;             if (prompt) { b += la; const float q = bf2f(QK[(size_t)row * 3072 + ch]), k = bf2f(QK[(size_t)row * 3072 + 512 + ch]);
;                 QD[(size_t)row * 512 + ch] = f2bf(q * __expf(b)); KI[(size_t)row * 512 + ch] = f2bf(k * __expf(-b)); }
;             else SA[(size_t)(row - TP) * 512 + ch] = __expf(la); }
.LBB0_1105:
	s_or_b64 exec, exec, s[16:17]
	s_waitcnt lgkmcnt(0)
	s_barrier
	s_mov_b32 s3, 0
	v_mov_b32_e32 v28, 0
	s_mov_b32 s5, 0
	s_and_b64 vcc, exec, s[10:11]
	s_cbranch_vccnz .Lgp_pre_done
	s_add_i32 s17, s14, 0
	v_mad_i64_i32 v[62:63], s[20:21], s17, v193, v[4:5]
	global_load_ushort v46, v[62:63], off
	global_load_ushort v47, v[62:63], off offset:1024
	s_add_i32 s17, s14, 1
	v_mad_i64_i32 v[62:63], s[20:21], s17, v193, v[4:5]
	global_load_ushort v48, v[62:63], off
	global_load_ushort v49, v[62:63], off offset:1024
	s_add_i32 s17, s14, 2
	v_mad_i64_i32 v[62:63], s[20:21], s17, v193, v[4:5]
	global_load_ushort v50, v[62:63], off
	global_load_ushort v51, v[62:63], off offset:1024
	s_add_i32 s17, s14, 3
	v_mad_i64_i32 v[62:63], s[20:21], s17, v193, v[4:5]
	global_load_ushort v52, v[62:63], off
	global_load_ushort v53, v[62:63], off offset:1024
.Lgp_pre_done:
	s_branch .LBB0_1107
.LBB0_1106:
	s_add_i32 s3, s3, 4
	s_addk_i32 s5, 0x100
	s_cmp_eq_u32 s2, s3
	s_cbranch_scc1 .LBB0_1123
.LBB0_1107:
	v_mov_b32_e32 v29, s5
	ds_read_b128 v[30:33], v29
	ds_read_b128 v[34:37], v29 offset:16
	ds_read_b128 v[38:41], v29 offset:32
	ds_read_b128 v[42:45], v29 offset:48
	s_add_i32 s16, s14, s3
	s_waitcnt vmcnt(15) lgkmcnt(3)
	v_mul_f32_e32 v29, v10, v31
	s_waitcnt vmcnt(11) lgkmcnt(2)
	v_mul_f32_e32 v31, v14, v35
	v_fmac_f32_e32 v29, v9, v30
	v_fmac_f32_e32 v29, v11, v32
	v_fmac_f32_e32 v31, v13, v34
	s_waitcnt vmcnt(7) lgkmcnt(1)
	v_mul_f32_e32 v30, v18, v39
	v_fmac_f32_e32 v29, v12, v33
	v_fmac_f32_e32 v31, v15, v36
	v_fmac_f32_e32 v30, v17, v38
	s_waitcnt vmcnt(0)
	s_and_b64 vcc, exec, s[10:11]
	s_cbranch_vccnz .Lgp_nopf
	v_mov_b32_e32 v54, v46
	v_mov_b32_e32 v55, v47
	v_mov_b32_e32 v56, v48
	v_mov_b32_e32 v57, v49
	v_mov_b32_e32 v58, v50
	v_mov_b32_e32 v59, v51
	v_mov_b32_e32 v60, v52
	v_mov_b32_e32 v61, v53
	s_add_i32 s17, s16, 4
	v_mad_i64_i32 v[62:63], s[20:21], s17, v193, v[4:5]
	global_load_ushort v46, v[62:63], off
	global_load_ushort v47, v[62:63], off offset:1024
	s_add_i32 s17, s16, 5
	v_mad_i64_i32 v[62:63], s[20:21], s17, v193, v[4:5]
	global_load_ushort v48, v[62:63], off
	global_load_ushort v49, v[62:63], off offset:1024
	s_add_i32 s17, s16, 6
	v_mad_i64_i32 v[62:63], s[20:21], s17, v193, v[4:5]
	global_load_ushort v50, v[62:63], off
	global_load_ushort v51, v[62:63], off offset:1024
	s_add_i32 s17, s16, 7
	v_mad_i64_i32 v[62:63], s[20:21], s17, v193, v[4:5]
	global_load_ushort v52, v[62:63], off
	global_load_ushort v53, v[62:63], off offset:1024
.Lgp_nopf:
	v_add_f32_e32 v29, v27, v29
	v_fmac_f32_e32 v31, v16, v37
	v_fmac_f32_e32 v30, v19, v40
	v_add_f32_e32 v29, v29, v31
	v_fmac_f32_e32 v30, v20, v41
	v_add_f32_e32 v29, v29, v30
	s_waitcnt lgkmcnt(0)
	v_mul_f32_e32 v30, v22, v43
	v_fmac_f32_e32 v30, v21, v42
	v_fmac_f32_e32 v30, v23, v44
	v_fmac_f32_e32 v30, v26, v45
	v_add_f32_e32 v29, v29, v30
	v_mul_f32_e64 v30, |v29|, s33
	v_exp_f32_e32 v30, v30
	v_min_f32_e32 v29, 0, v29
	s_mov_b64 s[18:19], -1
	v_add_f32_e32 v30, 1.0, v30
	v_cmp_gt_f32_e32 vcc, s84, v30
	s_nop 1
	v_cndmask_b32_e64 v31, 0, 32, vcc
	v_ldexp_f32 v30, v30, v31
	v_log_f32_e32 v30, v30
	s_nop 0
	v_mul_f32_e32 v31, 0x3f317217, v30
	v_fma_f32 v31, v30, s85, -v31
	v_fmac_f32_e32 v31, 0x3377d1cf, v30
	v_fmac_f32_e32 v31, 0x3f317217, v30
	v_cmp_lt_f32_e64 s[38:39], |v30|, s28
	s_nop 1
	v_cndmask_b32_e64 v30, v30, v31, s[38:39]
	v_cndmask_b32_e32 v31, 0, v194, vcc
	v_sub_f32_e32 v30, v30, v31
	v_sub_f32_e32 v29, v29, v30
	v_mul_f32_e32 v29, 0x3d800000, v29
	s_and_b64 vcc, exec, s[10:11]
	s_cbranch_vccz .LBB0_1109
	v_mul_f32_e32 v30, 0x3fb8aa3b, v29
	v_exp_f32_e32 v32, v30
	s_add_i32 s18, s16, 0xffffc000
	s_ashr_i32 s19, s18, 31
	s_lshl_b64 s[18:19], s[18:19], 11
	v_lshl_add_u64 v[30:31], v[2:3], 0, s[18:19]
	global_store_dword v[30:31], v32, off
	s_mov_b64 s[18:19], 0
.LBB0_1109:
	s_andn2_b64 vcc, exec, s[18:19]
	s_cbranch_vccnz .LBB0_1111
	v_mad_i64_i32 v[30:31], s[18:19], s16, v193, v[4:5]
	v_add_f32_e32 v28, v28, v29
	v_mov_b32_e32 v29, v54
	s_ashr_i32 s17, s16, 31
	v_mov_b32_e32 v30, v55
	s_lshl_b64 s[18:19], s[16:17], 10
	v_mov_b32_e32 v31, s19
	v_lshlrev_b32_e32 v29, 16, v29
	v_lshlrev_b32_e32 v34, 16, v30
	v_mul_f32_e32 v30, 0x3fb8aa3b, v28
	v_exp_f32_e32 v30, v30
	s_nop 0
	v_mul_f32_e32 v29, v30, v29
	v_lshl_or_b32 v30, v8, 1, s18
	v_cvt_pk_bf16_f32 v29, v29, s0
	v_lshl_add_u64 v[32:33], s[6:7], 0, v[30:31]
	global_store_short v[32:33], v29, off
	v_mul_f32_e32 v29, 0xbfb8aa3b, v28
	v_exp_f32_e32 v29, v29
	v_lshl_add_u64 v[30:31], s[8:9], 0, v[30:31]
	v_mul_f32_e32 v29, v29, v34
	v_cvt_pk_bf16_f32 v29, v29, s0
	global_store_short v[30:31], v29, off

; #define LAS __attribute__((address_space(3)))
; DI float bf2f(bf16_t b) { return __uint_as_float(((unsigned)b) << 16); }
; DI bf16_t f2bf(float f) { return (bf16_t)(pk2(f, 0.f) & 0xffffu); }
; DI void gla_prep(const Params& P, LAS unsigned char* lds) {
;     ...
;         for (int t = 0; t < nt; ++t) { const int row = row0 + t; float z = ba;
; #pragma unroll
;             for (int r4 = 0; r4 < 4; ++r4) { const f32x4 tv = *(const LAS f32x4*)(t16s + t * 16 + 4 * r4); z += tv[0] * w2[4 * r4] + tv[1] * w2[4 * r4 + 1] + tv[2] * w2[4 * r4 + 2] + tv[3] * w2[4 * r4 + 3]; }
;             const float la = (fminf(z, 0.f) - __logf(1.0f + __expf(-fabsf(z)))) * (1.f / 16.f);
;             if (prompt) { b += la; const float q = bf2f(QK[(size_t)row * 3072 + ch]), k = bf2f(QK[(size_t)row * 3072 + 512 + ch]);
;                 QD[(size_t)row * 512 + ch] = f2bf(q * __expf(b)); KI[(size_t)row * 512 + ch] = f2bf(k * __expf(-b)); }
;             else SA[(size_t)(row - TP) * 512 + ch] = __expf(la); }
.LBB0_1113:
	s_andn2_b64 vcc, exec, s[18:19]
	s_cbranch_vccnz .LBB0_1115
	s_add_i32 s18, s16, 1
	v_mad_i64_i32 v[30:31], s[20:21], s18, v193, v[4:5]
	v_add_f32_e32 v28, v28, v29
	v_mov_b32_e32 v29, v56
	s_ashr_i32 s19, s18, 31
	v_mov_b32_e32 v30, v57
	s_lshl_b64 s[18:19], s[18:19], 10
	v_mov_b32_e32 v31, s19
	v_lshlrev_b32_e32 v29, 16, v29
	v_lshlrev_b32_e32 v34, 16, v30
	v_mul_f32_e32 v30, 0x3fb8aa3b, v28
	v_exp_f32_e32 v30, v30
	s_nop 0
	v_mul_f32_e32 v29, v30, v29
	v_lshl_or_b32 v30, v8, 1, s18
	v_cvt_pk_bf16_f32 v29, v29, s0
	v_lshl_add_u64 v[32:33], s[6:7], 0, v[30:31]
	global_store_short v[32:33], v29, off
	v_mul_f32_e32 v29, 0xbfb8aa3b, v28
	v_exp_f32_e32 v29, v29
	v_lshl_add_u64 v[30:31], s[8:9], 0, v[30:31]
	v_mul_f32_e32 v29, v29, v34
	v_cvt_pk_bf16_f32 v29, v29, s0
	global_store_short v[30:31], v29, off

; #define LAS __attribute__((address_space(3)))
; DI float bf2f(bf16_t b) { return __uint_as_float(((unsigned)b) << 16); }
; DI bf16_t f2bf(float f) { return (bf16_t)(pk2(f, 0.f) & 0xffffu); }
; DI void gla_prep(const Params& P, LAS unsigned char* lds) {
;     ...
;         for (int t = 0; t < nt; ++t) { const int row = row0 + t; float z = ba;
; #pragma unroll
;             for (int r4 = 0; r4 < 4; ++r4) { const f32x4 tv = *(const LAS f32x4*)(t16s + t * 16 + 4 * r4); z += tv[0] * w2[4 * r4] + tv[1] * w2[4 * r4 + 1] + tv[2] * w2[4 * r4 + 2] + tv[3] * w2[4 * r4 + 3]; }
;             const float la = (fminf(z, 0.f) - __logf(1.0f + __expf(-fabsf(z)))) * (1.f / 16.f);
;             if (prompt) { b += la; const float q = bf2f(QK[(size_t)row * 3072 + ch]), k = bf2f(QK[(size_t)row * 3072 + 512 + ch]);
;                 QD[(size_t)row * 512 + ch] = f2bf(q * __expf(b)); KI[(size_t)row * 512 + ch] = f2bf(k * __expf(-b)); }
;             else SA[(size_t)(row - TP) * 512 + ch] = __expf(la); }
.LBB0_1117:
	s_andn2_b64 vcc, exec, s[18:19]
	s_cbranch_vccnz .LBB0_1119
	s_add_i32 s18, s16, 2
	v_mad_i64_i32 v[30:31], s[20:21], s18, v193, v[4:5]
	v_add_f32_e32 v28, v28, v29
	v_mov_b32_e32 v29, v58
	s_ashr_i32 s19, s18, 31
	v_mov_b32_e32 v30, v59
	s_lshl_b64 s[18:19], s[18:19], 10
	v_mov_b32_e32 v31, s19
	v_lshlrev_b32_e32 v29, 16, v29
	v_lshlrev_b32_e32 v34, 16, v30
	v_mul_f32_e32 v30, 0x3fb8aa3b, v28
	v_exp_f32_e32 v30, v30
	s_nop 0
	v_mul_f32_e32 v29, v30, v29
	v_lshl_or_b32 v30, v8, 1, s18
	v_cvt_pk_bf16_f32 v29, v29, s0
	v_lshl_add_u64 v[32:33], s[6:7], 0, v[30:31]
	global_store_short v[32:33], v29, off
	v_mul_f32_e32 v29, 0xbfb8aa3b, v28
	v_exp_f32_e32 v29, v29
	v_lshl_add_u64 v[30:31], s[8:9], 0, v[30:31]
	v_mul_f32_e32 v29, v29, v34
	v_cvt_pk_bf16_f32 v29, v29, s0
	global_store_short v[30:31], v29, off

; #define LAS __attribute__((address_space(3)))
; DI float bf2f(bf16_t b) { return __uint_as_float(((unsigned)b) << 16); }
; DI bf16_t f2bf(float f) { return (bf16_t)(pk2(f, 0.f) & 0xffffu); }
; DI void gla_prep(const Params& P, LAS unsigned char* lds) {
;     ...
;         for (int t = 0; t < nt; ++t) { const int row = row0 + t; float z = ba;
; #pragma unroll
;             for (int r4 = 0; r4 < 4; ++r4) { const f32x4 tv = *(const LAS f32x4*)(t16s + t * 16 + 4 * r4); z += tv[0] * w2[4 * r4] + tv[1] * w2[4 * r4 + 1] + tv[2] * w2[4 * r4 + 2] + tv[3] * w2[4 * r4 + 3]; }
;             const float la = (fminf(z, 0.f) - __logf(1.0f + __expf(-fabsf(z)))) * (1.f / 16.f);
;             if (prompt) { b += la; const float q = bf2f(QK[(size_t)row * 3072 + ch]), k = bf2f(QK[(size_t)row * 3072 + 512 + ch]);
;                 QD[(size_t)row * 512 + ch] = f2bf(q * __expf(b)); KI[(size_t)row * 512 + ch] = f2bf(k * __expf(-b)); }
;             else SA[(size_t)(row - TP) * 512 + ch] = __expf(la); }
.LBB0_1122:
	s_add_i32 s16, s16, 3
	v_mad_i64_i32 v[30:31], s[18:19], s16, v193, v[4:5]
	v_add_f32_e32 v28, v28, v29
	v_mov_b32_e32 v29, v60
	s_ashr_i32 s17, s16, 31
	v_mov_b32_e32 v30, v61
	s_lshl_b64 s[16:17], s[16:17], 10
	v_mov_b32_e32 v31, s17
	v_lshlrev_b32_e32 v29, 16, v29
	v_lshlrev_b32_e32 v34, 16, v30
	v_mul_f32_e32 v30, 0x3fb8aa3b, v28
	v_exp_f32_e32 v30, v30
	s_nop 0
	v_mul_f32_e32 v29, v30, v29
	v_lshl_or_b32 v30, v8, 1, s16
	v_cvt_pk_bf16_f32 v29, v29, s0
	v_lshl_add_u64 v[32:33], s[6:7], 0, v[30:31]
	global_store_short v[32:33], v29, off
	v_mul_f32_e32 v29, 0xbfb8aa3b, v28
	v_exp_f32_e32 v29, v29
	v_lshl_add_u64 v[30:31], s[8:9], 0, v[30:31]
	v_mul_f32_e32 v29, v29, v34
	v_cvt_pk_bf16_f32 v29, v29, s0
	global_store_short v[30:31], v29, off
	s_branch .LBB0_1106
